# grid barrier: non-leader workgroups pre-clean the XCD L2 (early buffer_wbl2) before spinning
# baseline (speedup 1.0000x reference)
.LBB0_963:
	s_or_b64 exec, exec, s[2:3]
	v_cvt_f32_u32_e32 v4, v2
	s_waitcnt vmcnt(0)
	v_readfirstlane_b32 s2, v3
	v_sub_u32_e32 v3, 0, v2
	v_rcp_iflag_f32_e32 v4, v4
	v_add_u32_e32 v5, s2, v1
	v_mul_f32_e32 v4, 0x4f7ffffe, v4
	v_cvt_u32_f32_e32 v4, v4
	v_mul_lo_u32 v1, v3, v4
	v_mul_hi_u32 v1, v4, v1
	v_add_u32_e32 v1, v4, v1
	v_mul_hi_u32 v1, v5, v1
	v_mul_lo_u32 v3, v1, v2
	v_sub_u32_e32 v3, v5, v3
	v_add_u32_e32 v4, 1, v1
	v_cmp_ge_u32_e32 vcc, v3, v2
	s_nop 1
	v_cndmask_b32_e32 v1, v1, v4, vcc
	v_sub_u32_e32 v4, v3, v2
	v_cndmask_b32_e32 v3, v3, v4, vcc
	v_add_u32_e32 v4, 1, v1
	v_cmp_ge_u32_e32 vcc, v3, v2
	v_add_u32_e32 v3, 1, v5
	s_nop 0
	v_cndmask_b32_e32 v1, v1, v4, vcc
	v_mul_lo_u32 v4, v2, v1
	v_add_u32_e32 v2, v4, v2
	v_cmp_ne_u32_e32 vcc, v3, v2
	s_and_saveexec_b64 s[2:3], vcc
	s_xor_b64 s[2:3], exec, s[2:3]
	s_cbranch_execz .LBB0_977
	buffer_wbl2 sc1
	v_readlane_b32 s6, v253, 43
	v_readlane_b32 s7, v253, 44
	s_waitcnt lgkmcnt(0)
	s_nop 3
	global_load_dword v0, v65, s[6:7] sc1
	s_waitcnt vmcnt(0)
	v_cmp_eq_u32_e32 vcc, v0, v1
	s_and_saveexec_b64 s[22:23], vcc
	s_cbranch_execz .LBB0_976
	s_mov_b32 s5, 1
	s_mov_b64 s[28:29], 0
	s_branch .LBB0_967
